# attention queue: next-item atomic fetch no longer waited at issue; picked up at the next loop top
# speedup vs baseline: 1.0101x; 1.0101x over previous
.LBB0_261:
	s_or_b64 exec, exec, s[0:1]
	v_mov_b32_e32 v245, v171
	s_add_u32 s12, s38, 0x500000
	s_addc_u32 s13, s39, 0
	s_add_u32 s14, s38, 0xbb62c00
	s_addc_u32 s15, s39, 0
	s_add_u32 s18, s38, 0xbb63800
	s_addc_u32 s19, s39, 0
	s_add_i32 s27, 0, 0x22000
	s_mov_b64 s[22:23], 0
	s_mov_b32 s21, 0
	v_mov_b32_e32 v173, s27
	v_mov_b32_e32 v1, 0
	s_movk_i32 s62, 0x5800
	s_mov_b64 s[24:25], 0x800
	s_movk_i32 s63, 0x1ff
	s_add_i32 s64, 0, 0x20000
	s_movk_i32 s65, 0x1000
	s_mov_b32 s26, 0x3b800000
	s_add_i32 s97, 0, 0x20800
	s_mov_b32 s67, 0xf149f2ca
	s_mov_b32 s68, 0xffff0000
	s_movk_i32 s69, 0x50
	s_movk_i32 s70, 0x60
	s_movk_i32 s71, 0x70
	s_movk_i32 s72, 0x80
	s_movk_i32 s73, 0x90
	s_movk_i32 s79, 0xa0
	s_movk_i32 s80, 0xb0
	s_movk_i32 s81, 0xc0
	s_movk_i32 s82, 0xd0
	s_movk_i32 s83, 0xe0
	s_movk_i32 s84, 0xf0
	s_movk_i32 s85, 0x1400
	s_movk_i32 s86, 0x5000
	s_mov_b64 s[48:49], 0xa000
	s_movk_i32 s87, 0x210
	s_movk_i32 s88, 0x81
	s_mov_b64 s[50:51], 0x160000
	v_mov_b32_e32 v188, 0x16000
	v_mov_b32_e32 v189, 0x2c000
	v_mov_b32_e32 v190, 0x42000
	v_mov_b32_e32 v191, 0x58000
	v_mov_b32_e32 v192, 0x6e000
	v_mov_b32_e32 v193, 0x84000
	v_mov_b32_e32 v194, 0x9a000
	v_mov_b32_e32 v195, 0xf149f2ca
	v_mov_b32_e32 v196, 0x14000
	v_mov_b32_e32 v197, 0x19000
	v_mov_b32_e32 v198, 0x1e000
	v_mov_b32_e32 v199, 0x23000
	v_writelane_b32 v244, s97, 2
	s_branch .LBB0_265

.LBB0_265:
	s_barrier
	s_and_saveexec_b64 s[0:1], s[4:5]
	s_waitcnt vmcnt(12)
	v_mov_b32_e32 v171, v245
	v_mov_b32_e32 v0, s27
	ds_write_b32 v0, v171
	s_or_b64 exec, exec, s[0:1]
	s_waitcnt lgkmcnt(0)
	s_barrier
	ds_read_b32 v0, v173
	s_movk_i32 s0, 0x6ff
	s_waitcnt lgkmcnt(0)
	v_cmp_lt_i32_e32 vcc, s0, v0
	v_readfirstlane_b32 s89, v0
	s_mov_b64 s[0:1], -1
	s_cbranch_vccnz .LBB0_264
	s_and_saveexec_b64 s[0:1], s[4:5]
	s_cbranch_execz .LBB0_272
	s_mov_b64 s[52:53], exec
	v_mbcnt_lo_u32_b32 v0, s52, 0
	v_mbcnt_hi_u32_b32 v0, s53, v0
	v_cmp_eq_u32_e32 vcc, 0, v0
	s_and_saveexec_b64 s[2:3], vcc
	s_cbranch_execz .LBB0_271
	s_bcnt1_i32_b64 s20, s[52:53]
	v_mov_b32_e32 v2, s20
	global_atomic_add v245, v1, v2, s[38:39] offset:256 sc0
.LBB0_271:
	s_or_b64 exec, exec, s[2:3]
.LBB0_272:
	s_or_b64 exec, exec, s[0:1]
	s_xor_b64 s[0:1], s[22:23], -1
	s_cmpk_gt_i32 s89, 0xbf
	s_mov_b64 s[52:53], -1
	s_cbranch_scc0 .LBB0_438
	s_cmpk_gt_u32 s89, 0x17f
	s_cbranch_scc0 .LBB0_401
	s_cmpk_gt_u32 s89, 0x47f
	s_cbranch_scc0 .LBB0_317
	s_cmpk_gt_u32 s89, 0x67f
	s_mov_b64 s[2:3], -1
	s_cbranch_scc0 .LBB0_305
	s_add_i32 s2, s89, 0xfffff980
	s_lshr_b32 s2, s2, 6
	v_mov_b32_e32 v2, v175
	s_bfe_u32 s56, s89, 0x30003
	s_sub_i32 s94, 1, s2
	s_lshl_b32 s20, s94, 8
	v_readfirstlane_b32 s2, v2
	s_ashr_i32 s58, s2, 6
	s_lshl_b32 s2, s56, 11
	s_or_b32 s54, s20, s2
	s_mul_i32 s2, s54, 0x5800
	s_add_u32 s2, s6, s2
	s_addc_u32 s3, s7, 0
	s_lshl_b32 s52, s89, 7
	s_and_b32 s57, s52, 0x380
	s_lshl_b32 s90, s57, 1
	s_add_u32 s2, s2, s90
	s_addc_u32 s3, s3, 0
	s_mul_i32 s52, s56, 0x2c00000
	s_add_u32 s52, s6, s52
	v_and_b32_e32 v11, 31, v2
	s_addc_u32 s53, s7, 0
	s_lshl_b32 s66, s58, 5
	v_or_b32_e32 v172, s66, v11
	v_mov_b64_e32 v[4:5], s[2:3]
	s_add_u32 s52, s52, s90
	v_mad_i64_i32 v[4:5], s[2:3], v172, s62, v[4:5]
	s_addc_u32 s53, s53, 0
	s_add_u32 s2, s52, 0x1000
	s_addc_u32 s3, s53, 0
	s_lshl_b32 s55, s58, 13
	s_add_i32 s59, s55, 0
	s_add_i32 s91, s59, 0x10000
	s_ashr_i32 s55, s66, 31
	s_add_u32 s92, s54, s66
	s_addc_u32 s93, 0, s55
	s_mul_i32 s54, s93, 0x5800
	s_mul_hi_u32 s55, s92, 0x5800
	s_add_i32 s55, s55, s54
	s_mul_i32 s54, s92, 0x5800
	s_add_u32 s54, s6, s54
	s_addc_u32 s55, s7, s55
	s_add_u32 s54, s54, s90
	v_bfe_u32 v10, v2, 5, 1
	s_addc_u32 s55, s55, 0
	v_lshlrev_b32_e32 v0, 4, v10
	s_add_u32 s54, s54, 0x1800
	v_bfe_u32 v170, v2, 4, 2
	v_lshl_add_u64 v[4:5], v[4:5], 0, v[0:1]
	s_addc_u32 s55, s55, 0
	v_xor_b32_e32 v3, v170, v2
	v_mul_u32_u24_e32 v0, 0x5800, v170
	global_load_dwordx4 v[112:115], v[4:5], off
	global_load_dwordx4 v[116:119], v[4:5], off offset:32
	global_load_dwordx4 v[120:123], v[4:5], off offset:64
	global_load_dwordx4 v[124:127], v[4:5], off offset:96
	global_load_dwordx4 v[128:131], v[4:5], off offset:128
	global_load_dwordx4 v[132:135], v[4:5], off offset:160
	global_load_dwordx4 v[136:139], v[4:5], off offset:192
	global_load_dwordx4 v[140:143], v[4:5], off offset:224
	v_lshl_add_u64 v[4:5], s[54:55], 0, v[0:1]
	v_lshlrev_b32_e32 v0, 3, v3
	v_and_b32_e32 v0, 0x78, v0
	v_lshlrev_b32_e32 v144, 1, v0
	v_mov_b32_e32 v145, v1
	v_lshl_add_u64 v[4:5], v[4:5], 0, v[144:145]
	s_mov_b32 m0, s91
	v_bitop3_b32 v3, v170, v2, 4 bitop3:0x36
	v_mad_u32_u24 v0, v170, s62, v188
	global_load_lds_dwordx4 v[4:5], off
	v_lshl_add_u64 v[4:5], s[54:55], 0, v[0:1]
	v_lshlrev_b32_e32 v0, 3, v3
	v_and_b32_e32 v0, 0x78, v0
	v_lshlrev_b32_e32 v146, 1, v0
	v_mov_b32_e32 v147, v1
	v_lshl_add_u64 v[4:5], v[4:5], 0, v[146:147]
	s_add_i32 m0, s59, 0x10400
	v_bitop3_b32 v3, v170, v2, 8 bitop3:0x36
	v_mad_u32_u24 v0, v170, s62, v189
	global_load_lds_dwordx4 v[4:5], off
	v_lshl_add_u64 v[4:5], s[54:55], 0, v[0:1]
	v_lshlrev_b32_e32 v0, 3, v3
	v_and_b32_e32 v0, 0x78, v0
	v_lshlrev_b32_e32 v148, 1, v0
	v_mov_b32_e32 v149, v1
	v_lshl_add_u64 v[4:5], v[4:5], 0, v[148:149]
	s_add_i32 m0, s59, 0x10800
	v_bitop3_b32 v3, v170, v2, 12 bitop3:0x36
	v_mad_u32_u24 v0, v170, s62, v190
	global_load_lds_dwordx4 v[4:5], off
	v_lshl_add_u64 v[4:5], s[54:55], 0, v[0:1]
	v_lshlrev_b32_e32 v0, 3, v3
	v_and_b32_e32 v0, 0x78, v0
	v_lshlrev_b32_e32 v152, 1, v0
	v_mov_b32_e32 v153, v1
	v_lshl_add_u64 v[4:5], v[4:5], 0, v[152:153]
	s_add_i32 m0, s59, 0x10c00
	v_mad_u32_u24 v0, v170, s62, v191
	global_load_lds_dwordx4 v[4:5], off
	v_lshl_add_u64 v[4:5], s[54:55], 0, v[0:1]
	v_lshl_add_u64 v[4:5], v[4:5], 0, v[144:145]
	s_add_i32 m0, s59, 0x11000
	v_bitop3_b32 v3, v170, v2, 20 bitop3:0x36
	v_mad_u32_u24 v0, v170, s62, v192
	global_load_lds_dwordx4 v[4:5], off
	v_lshl_add_u64 v[4:5], s[54:55], 0, v[0:1]
	v_lshlrev_b32_e32 v0, 3, v3
	v_and_b32_e32 v0, 0x78, v0
	v_lshlrev_b32_e32 v150, 1, v0
	v_mov_b32_e32 v151, v1
	v_lshl_add_u64 v[4:5], v[4:5], 0, v[150:151]
	s_add_i32 m0, s59, 0x11400
	v_bitop3_b32 v3, v170, v2, 24 bitop3:0x36
	v_mad_u32_u24 v0, v170, s62, v193
	global_load_lds_dwordx4 v[4:5], off
	v_lshl_add_u64 v[4:5], s[54:55], 0, v[0:1]
	v_lshlrev_b32_e32 v0, 3, v3
	v_and_b32_e32 v0, 0x78, v0
	v_lshlrev_b32_e32 v154, 1, v0
	v_mov_b32_e32 v155, v1
	v_lshl_add_u64 v[4:5], v[4:5], 0, v[154:155]
	s_add_i32 m0, s59, 0x11800
	v_bitop3_b32 v3, v170, v2, 28 bitop3:0x36
	v_mad_u32_u24 v0, v170, s62, v194
	global_load_lds_dwordx4 v[4:5], off
	v_lshl_add_u64 v[4:5], s[54:55], 0, v[0:1]
	v_lshlrev_b32_e32 v0, 3, v3
	v_and_b32_e32 v0, 0x78, v0
	s_lshl_b32 s54, s58, 3
	v_lshlrev_b32_e32 v156, 1, v0
	v_mov_b32_e32 v157, v1
	v_or_b32_e32 v158, s54, v170
	v_lshl_add_u64 v[4:5], v[4:5], 0, v[156:157]
	s_add_i32 m0, s59, 0x11c00
	s_lshl_b32 s95, s58, 11
	v_bitop3_b32 v0, s54, v2, v170 bitop3:0x36
	s_lshl_b32 s58, s58, 1
	v_ashrrev_i32_e32 v159, 31, v158
	global_load_lds_dwordx4 v[4:5], off
	v_and_b32_e32 v145, 15, v2
	v_lshlrev_b32_e32 v3, 2, v170
	s_and_b32 s54, s58, 2
	v_lshl_add_u64 v[4:5], v[158:159], 0, s[20:21]
	v_mov_b64_e32 v[6:7], s[52:53]
	v_lshlrev_b32_e32 v0, 3, v0
	v_bitop3_b32 v12, s54, v145, v3 bitop3:0x36
	v_mad_u64_u32 v[8:9], s[54:55], v4, s62, v[6:7]
	v_and_b32_e32 v0, 0x78, v0
	v_mad_i32_i24 v9, v5, s62, v9
	v_lshlrev_b32_e32 v0, 1, v0
	v_lshl_add_u64 v[8:9], v[8:9], 0, v[0:1]
	s_add_i32 s59, s95, 0
	v_lshl_add_u64 v[8:9], v[8:9], 0, s[24:25]
	s_mov_b32 m0, s59
	s_or_b32 s58, s58, 1
	global_load_lds_dwordx4 v[8:9], off
	v_mov_b64_e32 v[8:9], s[2:3]
	v_mad_u64_u32 v[14:15], s[54:55], v4, s62, v[8:9]
	v_mad_i32_i24 v15, v5, s62, v15
	v_lshlrev_b32_e32 v4, 4, v12
	v_mov_b32_e32 v5, v1
	s_lshl_b32 s54, s58, 2
	v_lshl_add_u64 v[4:5], v[14:15], 0, v[4:5]
	s_add_i32 m0, s59, 0x8000
	v_or_b32_e32 v160, s54, v170
	global_load_lds_dwordx4 v[4:5], off
	v_bitop3_b32 v4, s54, v2, v170 bitop3:0x36
	s_and_b32 s54, s58, 3
	v_ashrrev_i32_e32 v161, 31, v160
	v_bitop3_b32 v13, s54, v145, v3 bitop3:0x36
	v_lshl_add_u64 v[14:15], v[160:161], 0, s[20:21]
	v_lshlrev_b32_e32 v3, 3, v4
	v_mad_u64_u32 v[6:7], s[54:55], v14, s62, v[6:7]
	v_and_b32_e32 v3, 0x78, v3
	v_mad_i32_i24 v7, v15, s62, v7
	v_lshlrev_b32_e32 v4, 1, v3
	v_mov_b32_e32 v5, v1
	s_lshl_b32 s96, s58, 10
	v_lshl_add_u64 v[6:7], v[6:7], 0, v[4:5]
	s_add_i32 s58, s96, 0
	v_lshl_add_u64 v[6:7], v[6:7], 0, s[24:25]
	s_mov_b32 m0, s58
	s_lshl_b32 s75, s94, 7
	global_load_lds_dwordx4 v[6:7], off
	v_mad_u64_u32 v[6:7], s[54:55], v14, s62, v[8:9]
	v_mad_i32_i24 v7, v15, s62, v7
	v_lshlrev_b32_e32 v8, 4, v13
	v_mov_b32_e32 v9, v1
	v_lshl_add_u64 v[6:7], v[6:7], 0, v[8:9]
	s_add_i32 m0, s58, 0x8000
	v_cmp_gt_i32_e32 vcc, s75, v2
	global_load_lds_dwordx4 v[6:7], off
	s_and_saveexec_b64 s[54:55], vcc
	s_cbranch_execz .LBB0_289
	v_and_b32_e32 v3, 0x7f, v2
	s_lshl_b32 s76, s56, 3
	s_lshl_b32 s56, s57, 2
	v_lshlrev_b32_e32 v6, 2, v3
	v_add_u32_e32 v3, 0x200, v2
	s_add_u32 s56, s77, s56
	v_max_i32_e32 v8, s75, v3
	s_addc_u32 s57, s78, 0
	v_mov_b32_e32 v7, v1
	v_xad_u32 v9, v2, -1, v8
	v_lshl_add_u64 v[6:7], s[56:57], 0, v[6:7]
	v_cmp_lt_u32_e32 vcc, s63, v9
	s_mov_b64 s[58:59], -1
	v_mov_b32_e32 v8, v2
	s_and_saveexec_b64 s[56:57], vcc
	s_cbranch_execz .LBB0_286
	v_lshrrev_b32_e32 v14, 9, v9
	v_add_u32_e32 v8, -1, v14
	v_lshrrev_b32_e32 v9, 1, v8
	v_add_u32_e32 v15, 1, v9
	v_cmp_lt_u32_e32 vcc, 5, v8
	v_mov_b32_e32 v18, 0
	v_mov_b64_e32 v[8:9], v[2:3]
	s_and_saveexec_b64 s[58:59], vcc
	s_cbranch_execz .LBB0_282
	v_and_b32_e32 v16, -4, v15
	v_lshl_add_u32 v17, v2, 2, s64
	s_mov_b32 s97, 0
	s_mov_b64 s[60:61], 0
	v_mov_b64_e32 v[8:9], v[2:3]
